# in-proj: next tile A1 K-tile-1 piece staged before epilogue stores, three vmcnt waits of peeled first iteration relaxed so output-store burst drains under the next K-loop
# speedup vs baseline: 1.0140x; 1.0039x over previous
.LBB0_374:
	s_add_u32 s42, s46, 0x80
	s_addc_u32 s43, s47, 0
	s_add_u32 s46, s0, 0x100
	s_addc_u32 s47, s1, 0
	s_mov_b32 s0, 0
	s_add_i32 s97, s0, 2
	s_add_u32 s2, s42, 0x80
	s_addc_u32 s1, s43, 0
	s_add_i32 s12, 0, 0x10000
	s_cmp_eq_u32 s13, s0
	s_cselect_b32 s1, s95, s1
	s_cselect_b32 s0, s94, s2
	s_cselect_b32 s15, s55, s47
	s_cselect_b32 s14, s54, s46
	s_add_i32 s2, 0, 0x14000
	v_add_u32_e32 v140, s12, v195
	v_add_u32_e32 v174, s2, v195
	ds_read_b128 v[128:131], v140
	ds_read_b128 v[132:135], v140 offset:1024
	ds_read_b128 v[136:139], v140 offset:2048
	ds_read_b128 v[140:143], v140 offset:3072
	ds_read_b128 v[144:147], v174
	ds_read_b128 v[148:151], v174 offset:1024
	ds_read_b128 v[170:173], v174 offset:2048
	ds_read_b128 v[174:177], v174 offset:3072
	ds_read_b128 v[178:181], v157
	ds_read_b128 v[202:205], v157 offset:1024
	ds_read_b128 v[206:209], v157 offset:2048
	ds_read_b128 v[210:213], v157 offset:3072
	ds_read_b128 v[214:217], v157 offset:4096
	ds_read_b128 v[218:221], v157 offset:5120
	ds_read_b128 v[222:225], v157 offset:6144
	ds_read_b128 v[226:229], v157 offset:7168
	s_cmp_lg_u32 s18, 1
	s_cbranch_scc1 .Lpeel_noa1
	v_lshl_add_u64 v[230:231], s[42:43], 0, v[166:167]
	s_add_i32 m0, s45, 0xc000
	s_nop 0
	global_load_lds_dwordx4 v[230:231], off
	v_lshl_add_u64 v[230:231], s[42:43], 0, v[168:169]
	s_add_i32 m0, s45, 0xe000
	s_nop 0
	global_load_lds_dwordx4 v[230:231], off
.Lpeel_noa1:
	s_cmp_eq_u32 s18, 1
	s_cbranch_scc1 .Lpeel_strict375_1
	s_waitcnt vmcnt(16)
	s_branch .Lpeel_join375_1

.Lpeel_join375_2:
	s_waitcnt lgkmcnt(0)
	s_barrier
	s_setprio 1
	s_waitcnt lgkmcnt(0)
	v_mfma_f32_16x16x32_bf16 v[52:55], v[128:131], v[178:181], 0
	v_mfma_f32_16x16x32_bf16 v[48:51], v[136:139], v[178:181], 0
	v_mfma_f32_16x16x32_bf16 v[36:39], v[128:131], v[206:209], 0
	v_mfma_f32_16x16x32_bf16 v[32:35], v[136:139], v[206:209], 0
	v_mfma_f32_16x16x32_bf16 v[20:23], v[128:131], v[214:217], 0
	v_mfma_f32_16x16x32_bf16 v[16:19], v[136:139], v[214:217], 0
	v_mfma_f32_16x16x32_bf16 v[4:7], v[128:131], v[222:225], 0
	v_mfma_f32_16x16x32_bf16 v[0:3], v[136:139], v[222:225], 0
	v_mfma_f32_16x16x32_bf16 v[52:55], v[132:135], v[202:205], v[52:55]
	v_mfma_f32_16x16x32_bf16 v[48:51], v[140:143], v[202:205], v[48:51]
	v_mfma_f32_16x16x32_bf16 v[36:39], v[132:135], v[210:213], v[36:39]
	v_mfma_f32_16x16x32_bf16 v[32:35], v[140:143], v[210:213], v[32:35]
	v_mfma_f32_16x16x32_bf16 v[20:23], v[132:135], v[218:221], v[20:23]
	v_mfma_f32_16x16x32_bf16 v[16:19], v[140:143], v[218:221], v[16:19]
	v_mfma_f32_16x16x32_bf16 v[4:7], v[132:135], v[226:229], v[4:7]
	v_mfma_f32_16x16x32_bf16 v[0:3], v[140:143], v[226:229], v[0:3]
	s_setprio 0
	s_setprio 1
	v_mfma_f32_16x16x32_bf16 v[60:63], v[144:147], v[178:181], 0
	v_mfma_f32_16x16x32_bf16 v[56:59], v[170:173], v[178:181], 0
	v_mfma_f32_16x16x32_bf16 v[44:47], v[144:147], v[206:209], 0
	v_mfma_f32_16x16x32_bf16 v[40:43], v[170:173], v[206:209], 0
	v_mfma_f32_16x16x32_bf16 v[28:31], v[144:147], v[214:217], 0
	v_mfma_f32_16x16x32_bf16 v[24:27], v[170:173], v[214:217], 0
	v_mfma_f32_16x16x32_bf16 v[12:15], v[144:147], v[222:225], 0
	v_mfma_f32_16x16x32_bf16 v[8:11], v[170:173], v[222:225], 0
	v_mfma_f32_16x16x32_bf16 v[60:63], v[148:151], v[202:205], v[60:63]
	v_mfma_f32_16x16x32_bf16 v[56:59], v[174:177], v[202:205], v[56:59]
	v_mfma_f32_16x16x32_bf16 v[44:47], v[148:151], v[210:213], v[44:47]
	v_mfma_f32_16x16x32_bf16 v[40:43], v[174:177], v[210:213], v[40:43]
	v_mfma_f32_16x16x32_bf16 v[28:31], v[148:151], v[218:221], v[28:31]
	v_mfma_f32_16x16x32_bf16 v[24:27], v[174:177], v[218:221], v[24:27]
	v_mfma_f32_16x16x32_bf16 v[12:15], v[148:151], v[226:229], v[12:15]
	v_mfma_f32_16x16x32_bf16 v[8:11], v[174:177], v[226:229], v[8:11]
	s_setprio 0
	s_barrier
	s_add_i32 s2, 0, 0x18000
	s_add_i32 s12, 0, 0x1c000
	v_add_u32_e32 v140, s2, v195
	v_add_u32_e32 v174, s12, v195
	ds_read_b128 v[128:131], v140
	ds_read_b128 v[132:135], v140 offset:1024
	ds_read_b128 v[136:139], v140 offset:2048
	ds_read_b128 v[140:143], v140 offset:3072
	ds_read_b128 v[144:147], v174
	ds_read_b128 v[148:151], v174 offset:1024
	ds_read_b128 v[170:173], v174 offset:2048
	ds_read_b128 v[174:177], v174 offset:3072
	s_add_u32 s0, s0, s8
	s_addc_u32 s1, s1, s9
	s_mov_b32 m0, s28
	v_lshl_add_u64 v[242:243], s[0:1], 0, v[158:159]
	ds_read_b128 v[178:181], v157 offset:32768
	ds_read_b128 v[202:205], v157 offset:33792
	ds_read_b128 v[206:209], v157 offset:34816
	ds_read_b128 v[210:213], v157 offset:35840
	ds_read_b128 v[214:217], v157 offset:36864
	ds_read_b128 v[218:221], v157 offset:37888
	ds_read_b128 v[222:225], v157 offset:38912
	ds_read_b128 v[226:229], v157 offset:39936
	global_load_lds_dwordx4 v[242:243], off
	v_lshl_add_u64 v[242:243], s[0:1], 0, v[160:161]
	s_mov_b32 m0, s29
	s_nop 0
	global_load_lds_dwordx4 v[242:243], off
	s_cmp_eq_u32 s18, 1
	s_cbranch_scc1 .Lpeel_strict375_3
	s_waitcnt vmcnt(16)
	s_branch .Lpeel_join375_3

.Lpeel_join375_3:
	s_waitcnt lgkmcnt(0)
	s_barrier
	s_setprio 1
	s_waitcnt lgkmcnt(0)
	v_mfma_f32_16x16x32_bf16 v[120:123], v[128:131], v[178:181], v[120:123]
	v_mfma_f32_16x16x32_bf16 v[124:127], v[136:139], v[178:181], v[124:127]
	v_mfma_f32_16x16x32_bf16 v[100:103], v[128:131], v[206:209], v[100:103]
	v_mfma_f32_16x16x32_bf16 v[96:99], v[136:139], v[206:209], v[96:99]
	v_mfma_f32_16x16x32_bf16 v[84:87], v[128:131], v[214:217], v[84:87]
	v_mfma_f32_16x16x32_bf16 v[80:83], v[136:139], v[214:217], v[80:83]
	v_mfma_f32_16x16x32_bf16 v[68:71], v[128:131], v[222:225], v[68:71]
	v_mfma_f32_16x16x32_bf16 v[64:67], v[136:139], v[222:225], v[64:67]
	v_mfma_f32_16x16x32_bf16 v[120:123], v[132:135], v[202:205], v[120:123]
	v_mfma_f32_16x16x32_bf16 v[124:127], v[140:143], v[202:205], v[124:127]
	v_mfma_f32_16x16x32_bf16 v[100:103], v[132:135], v[210:213], v[100:103]
	v_mfma_f32_16x16x32_bf16 v[96:99], v[140:143], v[210:213], v[96:99]
	v_mfma_f32_16x16x32_bf16 v[84:87], v[132:135], v[218:221], v[84:87]
	v_mfma_f32_16x16x32_bf16 v[80:83], v[140:143], v[218:221], v[80:83]
	v_mfma_f32_16x16x32_bf16 v[68:71], v[132:135], v[226:229], v[68:71]
	v_mfma_f32_16x16x32_bf16 v[64:67], v[140:143], v[226:229], v[64:67]
	s_setprio 0
	s_setprio 1
	v_mfma_f32_16x16x32_bf16 v[116:119], v[144:147], v[178:181], v[116:119]
	v_mfma_f32_16x16x32_bf16 v[112:115], v[170:173], v[178:181], v[112:115]
	v_mfma_f32_16x16x32_bf16 v[108:111], v[144:147], v[206:209], v[108:111]
	v_mfma_f32_16x16x32_bf16 v[104:107], v[170:173], v[206:209], v[104:107]
	v_mfma_f32_16x16x32_bf16 v[92:95], v[144:147], v[214:217], v[92:95]
	v_mfma_f32_16x16x32_bf16 v[88:91], v[170:173], v[214:217], v[88:91]
	v_mfma_f32_16x16x32_bf16 v[76:79], v[144:147], v[222:225], v[76:79]
	v_mfma_f32_16x16x32_bf16 v[72:75], v[170:173], v[222:225], v[72:75]
	v_mfma_f32_16x16x32_bf16 v[116:119], v[148:151], v[202:205], v[116:119]
	v_mfma_f32_16x16x32_bf16 v[112:115], v[174:177], v[202:205], v[112:115]
	v_mfma_f32_16x16x32_bf16 v[108:111], v[148:151], v[210:213], v[108:111]
	v_mfma_f32_16x16x32_bf16 v[104:107], v[174:177], v[210:213], v[104:107]
	v_mfma_f32_16x16x32_bf16 v[92:95], v[148:151], v[218:221], v[92:95]
	v_mfma_f32_16x16x32_bf16 v[88:91], v[174:177], v[218:221], v[88:91]
	v_mfma_f32_16x16x32_bf16 v[76:79], v[148:151], v[226:229], v[76:79]
	v_mfma_f32_16x16x32_bf16 v[72:75], v[174:177], v[226:229], v[72:75]
	s_setprio 0
	s_barrier
	s_add_i32 s0, s2, s17
	v_lshl_add_u64 v[230:231], v[230:231], 0, s[36:37]
	s_mov_b32 m0, s0
	ds_read_b128 v[178:181], v157 offset:49152
	ds_read_b128 v[202:205], v157 offset:50176
	ds_read_b128 v[206:209], v157 offset:51200
	ds_read_b128 v[210:213], v157 offset:52224
	ds_read_b128 v[214:217], v157 offset:53248
	ds_read_b128 v[218:221], v157 offset:54272
	ds_read_b128 v[222:225], v157 offset:55296
	ds_read_b128 v[226:229], v157 offset:56320
	global_load_lds_dwordx4 v[230:231], off
	v_lshl_add_u64 v[230:231], v[232:233], 0, s[36:37]
	s_add_i32 m0, s0, 0x2000
	s_add_i32 s0, s12, s17
	global_load_lds_dwordx4 v[230:231], off
	v_lshl_add_u64 v[230:231], v[234:235], 0, s[36:37]
	s_mov_b32 m0, s0
	s_nop 0
	global_load_lds_dwordx4 v[230:231], off
	v_lshl_add_u64 v[230:231], v[236:237], 0, s[36:37]
	s_add_i32 m0, s0, 0x2000
	s_nop 0
	global_load_lds_dwordx4 v[230:231], off
	v_lshl_add_u64 v[230:231], v[238:239], 0, s[36:37]
	s_mov_b32 m0, s10
	s_nop 0
	global_load_lds_dwordx4 v[230:231], off
	v_lshl_add_u64 v[230:231], v[240:241], 0, s[36:37]
	s_mov_b32 m0, s11
	s_nop 0
	global_load_lds_dwordx4 v[230:231], off
	s_waitcnt vmcnt(8)
	s_waitcnt lgkmcnt(0)
	s_barrier
	s_setprio 1
	s_waitcnt lgkmcnt(0)
	v_mfma_f32_16x16x32_bf16 v[52:55], v[128:131], v[178:181], v[52:55]
	v_mfma_f32_16x16x32_bf16 v[48:51], v[136:139], v[178:181], v[48:51]
	v_mfma_f32_16x16x32_bf16 v[36:39], v[128:131], v[206:209], v[36:39]
	v_mfma_f32_16x16x32_bf16 v[32:35], v[136:139], v[206:209], v[32:35]
	v_mfma_f32_16x16x32_bf16 v[20:23], v[128:131], v[214:217], v[20:23]
	v_mfma_f32_16x16x32_bf16 v[16:19], v[136:139], v[214:217], v[16:19]
	v_mfma_f32_16x16x32_bf16 v[4:7], v[128:131], v[222:225], v[4:7]
	v_mfma_f32_16x16x32_bf16 v[0:3], v[136:139], v[222:225], v[0:3]
	v_mfma_f32_16x16x32_bf16 v[52:55], v[132:135], v[202:205], v[52:55]
	v_mfma_f32_16x16x32_bf16 v[48:51], v[140:143], v[202:205], v[48:51]
	v_mfma_f32_16x16x32_bf16 v[36:39], v[132:135], v[210:213], v[36:39]
	v_mfma_f32_16x16x32_bf16 v[32:35], v[140:143], v[210:213], v[32:35]
	v_mfma_f32_16x16x32_bf16 v[20:23], v[132:135], v[218:221], v[20:23]
	v_mfma_f32_16x16x32_bf16 v[16:19], v[140:143], v[218:221], v[16:19]
	v_mfma_f32_16x16x32_bf16 v[4:7], v[132:135], v[226:229], v[4:7]
	v_mfma_f32_16x16x32_bf16 v[0:3], v[140:143], v[226:229], v[0:3]
	s_setprio 0
	s_setprio 1
	v_mfma_f32_16x16x32_bf16 v[60:63], v[144:147], v[178:181], v[60:63]
	v_mfma_f32_16x16x32_bf16 v[56:59], v[170:173], v[178:181], v[56:59]
	v_mfma_f32_16x16x32_bf16 v[44:47], v[144:147], v[206:209], v[44:47]
	v_mfma_f32_16x16x32_bf16 v[40:43], v[170:173], v[206:209], v[40:43]
	v_mfma_f32_16x16x32_bf16 v[28:31], v[144:147], v[214:217], v[28:31]
	v_mfma_f32_16x16x32_bf16 v[24:27], v[170:173], v[214:217], v[24:27]
	v_mfma_f32_16x16x32_bf16 v[12:15], v[144:147], v[222:225], v[12:15]
	v_mfma_f32_16x16x32_bf16 v[8:11], v[170:173], v[222:225], v[8:11]
	v_mfma_f32_16x16x32_bf16 v[60:63], v[148:151], v[202:205], v[60:63]
	v_mfma_f32_16x16x32_bf16 v[56:59], v[174:177], v[202:205], v[56:59]
	v_mfma_f32_16x16x32_bf16 v[44:47], v[148:151], v[210:213], v[44:47]
	v_mfma_f32_16x16x32_bf16 v[40:43], v[174:177], v[210:213], v[40:43]
	v_mfma_f32_16x16x32_bf16 v[28:31], v[148:151], v[218:221], v[28:31]
	v_mfma_f32_16x16x32_bf16 v[24:27], v[174:177], v[218:221], v[24:27]
	v_mfma_f32_16x16x32_bf16 v[12:15], v[148:151], v[226:229], v[12:15]
	v_mfma_f32_16x16x32_bf16 v[8:11], v[174:177], v[226:229], v[8:11]
	s_setprio 0
	s_barrier
	s_add_u32 s42, s42, 0x100
	s_addc_u32 s43, s43, 0
	s_add_u32 s46, s46, 0x100
	s_addc_u32 s47, s47, 0
	s_cmp_ge_u32 s97, s31
	s_mov_b32 s0, s97

.LBB0_378:
	s_add_u32 s98, s94, 0x80
	s_addc_u32 s99, s95, 0
	v_lshl_add_u64 v[230:231], s[98:99], 0, v[166:167]
	s_add_i32 m0, s45, 0xc000
	s_nop 0
	global_load_lds_dwordx4 v[230:231], off
	v_lshl_add_u64 v[230:231], s[98:99], 0, v[168:169]
	s_add_i32 m0, s45, 0xe000
	s_nop 0
	global_load_lds_dwordx4 v[230:231], off
	s_mov_b64 s[0:1], -1
	s_and_b64 vcc, exec, s[78:79]
	s_cbranch_vccz .LBB0_385
	v_readlane_b32 s0, v244, 0
	v_readlane_b32 s1, v244, 1
	s_lshl_b32 s47, s23, 8
	s_andn2_b64 vcc, exec, s[0:1]
	s_mov_b32 s46, 0
	s_cbranch_vccnz .LBB0_384
	s_cmp_gt_i32 s23, 7
	s_mov_b64 s[0:1], -1
	s_cbranch_scc0 .LBB0_382
	s_cmp_gt_u32 s23, 19
	s_cselect_b64 s[0:1], -1, 0
	v_cndmask_b32_e64 v128, 0, 1, s[0:1]
	s_addk_i32 s47, 0xfc00
	s_mov_b64 s[0:1], 0
	v_readfirstlane_b32 s46, v128

	.amdhsa_kernel _Z8mega_fwd4Args
		.amdhsa_group_segment_fixed_size 0
		.amdhsa_private_segment_fixed_size 0
		.amdhsa_kernarg_size 400
		.amdhsa_user_sgpr_count 2
		.amdhsa_user_sgpr_dispatch_ptr 0
		.amdhsa_user_sgpr_queue_ptr 0
		.amdhsa_user_sgpr_kernarg_segment_ptr 1
		.amdhsa_user_sgpr_dispatch_id 0
		.amdhsa_user_sgpr_kernarg_preload_length 0
		.amdhsa_user_sgpr_kernarg_preload_offset 0
		.amdhsa_user_sgpr_private_segment_size 0
		.amdhsa_uses_dynamic_stack 0
		.amdhsa_enable_private_segment 0
		.amdhsa_system_sgpr_workgroup_id_x 1
		.amdhsa_system_sgpr_workgroup_id_y 0
		.amdhsa_system_sgpr_workgroup_id_z 0
		.amdhsa_system_sgpr_workgroup_info 0
		.amdhsa_system_vgpr_workitem_id 2
		.amdhsa_next_free_vgpr 248
		.amdhsa_next_free_sgpr 102
		.amdhsa_accum_offset 248
		.amdhsa_reserve_vcc 1
		.amdhsa_float_round_mode_32 0
		.amdhsa_float_round_mode_16_64 0
		.amdhsa_float_denorm_mode_32 3
		.amdhsa_float_denorm_mode_16_64 3
		.amdhsa_dx10_clamp 1
		.amdhsa_ieee_mode 1
		.amdhsa_fp16_overflow 0
		.amdhsa_tg_split 0
		.amdhsa_exception_fp_ieee_invalid_op 0
		.amdhsa_exception_fp_denorm_src 0
		.amdhsa_exception_fp_ieee_div_zero 0
		.amdhsa_exception_fp_ieee_overflow 0
		.amdhsa_exception_fp_ieee_underflow 0
		.amdhsa_exception_fp_ieee_inexact 0
		.amdhsa_exception_int_div_zero 0
	.end_amdhsa_kernel

amdhsa.kernels:
  - .agpr_count:     0
    .args:
      - .offset:         0
        .size:           144
        .value_kind:     by_value
      - .offset:         144
        .size:           4
        .value_kind:     hidden_block_count_x
      - .offset:         148
        .size:           4
        .value_kind:     hidden_block_count_y
      - .offset:         152
        .size:           4
        .value_kind:     hidden_block_count_z
      - .offset:         156
        .size:           2
        .value_kind:     hidden_group_size_x
      - .offset:         158
        .size:           2
        .value_kind:     hidden_group_size_y
      - .offset:         160
        .size:           2
        .value_kind:     hidden_group_size_z
      - .offset:         162
        .size:           2
        .value_kind:     hidden_remainder_x
      - .offset:         164
        .size:           2
        .value_kind:     hidden_remainder_y
      - .offset:         166
        .size:           2
        .value_kind:     hidden_remainder_z
      - .offset:         184
        .size:           8
        .value_kind:     hidden_global_offset_x
      - .offset:         192
        .size:           8
        .value_kind:     hidden_global_offset_y
      - .offset:         200
        .size:           8
        .value_kind:     hidden_global_offset_z
      - .offset:         208
        .size:           2
        .value_kind:     hidden_grid_dims
      - .offset:         232
        .size:           8
        .value_kind:     hidden_multigrid_sync_arg
      - .offset:         264
        .size:           4
        .value_kind:     hidden_dynamic_lds_size
    .group_segment_fixed_size: 0
    .kernarg_segment_align: 8
    .kernarg_segment_size: 400
    .language:       OpenCL C
    .language_version:
      - 2
      - 0
    .max_flat_workgroup_size: 512
    .name:           _Z8mega_fwd4Args
    .private_segment_fixed_size: 0
    .sgpr_count:     108
    .sgpr_spill_count: 222
    .symbol:         _Z8mega_fwd4Args.kd
    .uniform_work_group_size: 1
    .uses_dynamic_stack: false
    .vgpr_count:     248
    .vgpr_spill_count: 0
    .wavefront_size: 64
